# attention: redundant canonicalising self-max dropped from the row-max reductions
# baseline (speedup 1.0000x reference)
.LBB0_679:
	s_or_saveexec_b64 s[2:3], s[2:3]
	v_cndmask_b32_e64 v132, v186, v187, s[40:41]
	v_mul_f32_e32 v174, 0x3fb8aa3b, v132
	s_xor_b64 exec, exec, s[2:3]
	v_fma_f32 v16, v32, s36, v174
	v_fma_f32 v17, v33, s36, v174
	v_fma_f32 v12, v28, s36, v174
	v_fma_f32 v13, v29, s36, v174
	v_fma_f32 v8, v24, s36, v174
	v_fma_f32 v9, v25, s36, v174
	v_fma_f32 v4, v20, s36, v174
	v_fma_f32 v5, v21, s36, v174
	v_fma_f32 v14, v30, s36, v174
	v_fma_f32 v15, v31, s36, v174
	v_fma_f32 v10, v26, s36, v174
	v_fma_f32 v11, v27, s36, v174
	v_fma_f32 v6, v22, s36, v174
	v_fma_f32 v7, v23, s36, v174
	v_fma_f32 v2, v18, s36, v174
	v_fma_f32 v3, v19, s36, v174
	s_or_b64 exec, exec, s[2:3]
	v_max_f32_e32 v18, v2, v3
	v_max3_f32 v18, v18, v4, v5
	v_max3_f32 v18, v18, v6, v7
	v_max3_f32 v18, v18, v8, v9
	v_max3_f32 v18, v18, v10, v11
	v_max3_f32 v18, v18, v12, v13
	v_max3_f32 v18, v18, v14, v15
	v_max3_f32 v18, v18, v16, v17
	ds_bpermute_b32 v19, v35, v18
	s_waitcnt lgkmcnt(0)
	v_max_f32_e32 v194, v18, v19
	ds_bpermute_b32 v195, v149, v194
	ds_read_b128 v[18:21], v145 offset:8192
	ds_read_b128 v[22:25], v144 offset:12288
	ds_read_b128 v[26:29], v145 offset:8448
	ds_read_b128 v[30:33], v144 offset:12544
	ds_read_b128 v[246:249], v145 offset:8704
	ds_read_b128 v[250:253], v144 offset:12800
	s_waitcnt lgkmcnt(5)
	v_mfma_f32_16x16x32_f16 v[132:135], v[18:21], v[44:47], 0
	s_waitcnt lgkmcnt(4)
	v_mfma_f32_16x16x32_f16 v[132:135], v[22:25], v[48:51], v[132:135]
	ds_read_b128 v[18:21], v145 offset:8960
	ds_read_b128 v[22:25], v144 offset:13056
	s_waitcnt lgkmcnt(5)
	v_mfma_f32_16x16x32_f16 v[136:139], v[26:29], v[44:47], 0
	s_waitcnt lgkmcnt(4)
	v_mfma_f32_16x16x32_f16 v[136:139], v[30:33], v[48:51], v[136:139]
	s_waitcnt lgkmcnt(3)
	v_mfma_f32_16x16x32_f16 v[140:143], v[246:249], v[44:47], 0
	s_waitcnt lgkmcnt(2)
	v_mfma_f32_16x16x32_f16 v[140:143], v[250:253], v[48:51], v[140:143]
	s_waitcnt lgkmcnt(1)
	v_mfma_f32_16x16x32_f16 v[144:147], v[18:21], v[44:47], 0
	s_waitcnt lgkmcnt(0)
	v_mfma_f32_16x16x32_f16 v[144:147], v[22:25], v[48:51], v[144:147]
	s_and_saveexec_b64 s[2:3], vcc
	s_xor_b64 s[2:3], exec, s[2:3]
	s_cbranch_execz .LBB0_683
	s_nop 3
	v_lshl_add_u32 v18, v203, 2, s91
	v_lshl_add_u32 v19, v202, 2, s91
	v_lshl_add_u32 v20, v201, 2, s91
	v_lshl_add_u32 v21, v200, 2, s91
	v_lshl_add_u32 v22, v199, 2, s91
	v_lshl_add_u32 v23, v198, 2, s91
	v_lshl_add_u32 v24, v197, 2, s91
	v_lshl_add_u32 v25, v196, 2, s91
	v_lshl_add_u32 v26, v211, 2, s91
	v_lshl_add_u32 v27, v210, 2, s91
	v_lshl_add_u32 v28, v209, 2, s91
	v_lshl_add_u32 v29, v208, 2, s91
	v_lshl_add_u32 v30, v207, 2, s91
	v_lshl_add_u32 v31, v206, 2, s91
	v_lshl_add_u32 v32, v205, 2, s91
	v_lshl_add_u32 v33, v204, 2, s91
	ds_read_b32 v18, v18 offset:512
	ds_read_b32 v19, v19 offset:512
	ds_read_b32 v20, v20 offset:512
	ds_read_b32 v21, v21 offset:512
	ds_read_b32 v22, v22 offset:512
	ds_read_b32 v23, v23 offset:512
	ds_read_b32 v24, v24 offset:512
	ds_read_b32 v25, v25 offset:512
	ds_read_b32 v196, v26 offset:512
	ds_read_b32 v197, v27 offset:512
	ds_read_b32 v198, v28 offset:512
	ds_read_b32 v199, v29 offset:512
	ds_read_b32 v200, v30 offset:512
	ds_read_b32 v201, v31 offset:512
	ds_read_b32 v202, v32 offset:512
	ds_read_b32 v203, v33 offset:512
	s_waitcnt lgkmcnt(8)
	v_fma_f32 v32, v146, s36, v24
	v_fma_f32 v33, v147, s36, v25
	v_fma_f32 v30, v144, s36, v22
	v_fma_f32 v31, v145, s36, v23
	v_fma_f32 v28, v142, s36, v20
	v_fma_f32 v29, v143, s36, v21
	v_fma_f32 v26, v140, s36, v18
	v_fma_f32 v27, v141, s36, v19
	s_waitcnt lgkmcnt(0)
	v_fma_f32 v24, v138, s36, v202
	v_fma_f32 v25, v139, s36, v203
	v_fma_f32 v22, v136, s36, v200
	v_fma_f32 v23, v137, s36, v201
	v_fma_f32 v20, v134, s36, v198
	v_fma_f32 v21, v135, s36, v199
	v_fma_f32 v18, v132, s36, v196
	v_fma_f32 v19, v133, s36, v197
.LBB0_683:
	s_andn2_saveexec_b64 s[2:3], s[2:3]
	s_nop 3
	v_fma_f32 v32, v146, s36, v174
	v_fma_f32 v33, v147, s36, v174
	v_fma_f32 v28, v142, s36, v174
	v_fma_f32 v29, v143, s36, v174
	v_fma_f32 v24, v138, s36, v174
	v_fma_f32 v25, v139, s36, v174
	v_fma_f32 v20, v134, s36, v174
	v_fma_f32 v21, v135, s36, v174
	v_fma_f32 v30, v144, s36, v174
	v_fma_f32 v31, v145, s36, v174
	v_fma_f32 v26, v140, s36, v174
	v_fma_f32 v27, v141, s36, v174
	v_fma_f32 v22, v136, s36, v174
	v_fma_f32 v23, v137, s36, v174
	v_fma_f32 v18, v132, s36, v174
	v_fma_f32 v19, v133, s36, v174
	s_or_b64 exec, exec, s[2:3]
	v_max_f32_e32 v132, v18, v19
	v_max3_f32 v132, v132, v20, v21
	v_max3_f32 v132, v132, v22, v23
	v_max3_f32 v132, v132, v24, v25
	v_max3_f32 v132, v132, v26, v27
	v_max3_f32 v132, v132, v28, v29
	v_max3_f32 v132, v132, v30, v31
	v_max3_f32 v132, v132, v32, v33
	ds_bpermute_b32 v133, v35, v132
	s_waitcnt lgkmcnt(0)
	v_max_f32_e32 v132, v132, v133
	ds_bpermute_b32 v133, v149, v132
	s_add_i32 s2, s49, -1
	s_cmp_ge_i32 s2, s30
	s_cbranch_scc1 .LBB0_688
	s_xor_b32 s2, s50, 1
	v_lshl_add_u32 v134, s2, 14, v178
	s_waitcnt vmcnt(3)
	ds_write_b128 v134, v[72:75]
	s_waitcnt vmcnt(2)
	ds_write_b128 v134, v[80:83] offset:512
	s_mul_i32 s3, s2, 0x4800
	v_add_u32_e32 v134, s3, v226
	s_cmp_ge_i32 s49, s30
	s_waitcnt vmcnt(1)
	ds_write_b128 v134, v[84:87] offset:34816
	s_waitcnt vmcnt(0)
	ds_write_b128 v134, v[92:95] offset:34832
	s_cbranch_scc1 .LBB0_688
	v_add_co_u32_e32 v72, vcc, 0xfffc2000, v170
	s_nop 1
	v_addc_co_u32_e32 v73, vcc, -1, v171, vcc
	global_load_dwordx4 v[72:75], v[72:73], off
	s_nop 0
	global_load_dwordx4 v[80:83], v[170:171], off
	global_load_dwordx4 v[84:87], v[172:173], off offset:-16
	global_load_dwordx4 v[92:95], v[172:173], off
